# all WGs poll TOP>=(gen+1)*nx directly (XGEN publish hop removed) on top of v021 barrier trims
# baseline (speedup 1.0000x reference)
; DI unsigned xb_add(unsigned* p, unsigned v) { return __hip_atomic_fetch_add(p, v, __ATOMIC_RELAXED, __HIP_MEMORY_SCOPE_AGENT); }
; DI void xcd_barrier(unsigned* bar, volatile LAS unsigned* st) {
;     ...
;       __builtin_amdgcn_fence(__ATOMIC_ACQUIRE, "agent");
;       xb_add(&bar[XB_XGEN(x)], 1u);
;       asm volatile("s_waitcnt vmcnt(0)" ::: "memory");
.LBB0_320:
	s_or_b64 exec, exec, s[0:1]
	v_mov_b32_e32 v0, s3
	v_add_co_u32_e32 v2, vcc, 0x2000, v0
	v_mov_b32_e32 v0, s2
	s_nop 0
	v_addc_co_u32_e32 v3, vcc, 0, v0, vcc
	s_waitcnt vmcnt(0) lgkmcnt(0)
	buffer_inv sc1
	s_waitcnt vmcnt(0)

; DI unsigned xb_ld(unsigned* p) { return __hip_atomic_load(p, __ATOMIC_RELAXED, __HIP_MEMORY_SCOPE_AGENT); }
; DI unsigned xb_add(unsigned* p, unsigned v) { return __hip_atomic_fetch_add(p, v, __ATOMIC_RELAXED, __HIP_MEMORY_SCOPE_AGENT); }
; #define XB_SPIN(cond, bar) do { unsigned _sp = 0; while (cond) { __builtin_amdgcn_s_sleep(1); \
;     if ((++_sp & 255u) == 0u) { if (xb_ld(&(bar)[XB_TMO])) break; if (_sp > XB_SPIN_CAP) { atomicAdd(&(bar)[XB_TMO], 1u); break; } } } } while (0)
; DI void xcd_barrier(unsigned* bar, volatile LAS unsigned* st) {
;     ...
;     const unsigned old = xb_add(&bar[XB_XSUB(x)], 1u);
;     const unsigned gen = old / nloc;
;     if (old + 1u == (gen + 1u) * nloc) {
;       __builtin_amdgcn_fence(__ATOMIC_RELEASE, "agent");
;       asm volatile("s_waitcnt vmcnt(0)" ::: "memory");
;       const unsigned og = xb_add(&bar[XB_TOP], 1u);
;       const unsigned tg = og / nx;
;       if (og + 1u == (tg + 1u) * nx) xb_add(&bar[XB_TOPGEN], 1u);
;       else XB_SPIN(xb_ld(&bar[XB_TOPGEN]) == tg, bar);
;       __builtin_amdgcn_fence(__ATOMIC_ACQUIRE, "agent");
;       xb_add(&bar[XB_XGEN(x)], 1u);
;       asm volatile("s_waitcnt vmcnt(0)" ::: "memory");
;     } else {
;       XB_SPIN(xb_ld(&bar[XB_XGEN(x)]) == gen, bar);
.LBB0_350:
	s_lshl_b32 s0, s36, 8
	s_add_u32 s0, s58, s0
	s_addc_u32 s1, s59, 0
	v_mov_b32_e32 v3, s0
	v_add_co_u32_e32 v4, vcc, 0x22f21000, v3
	v_mov_b32_e32 v3, s1
	s_nop 0
	v_addc_co_u32_e32 v5, vcc, 0, v3, vcc
	flat_atomic_add v4, v[4:5], v187 offset:1024 sc0
	v_cvt_f32_u32_e32 v3, v2
	v_sub_u32_e32 v5, 0, v2
	s_add_u32 s25, s0, 0x22f20000
	s_addc_u32 s24, s1, 0
	v_rcp_iflag_f32_e32 v3, v3
	s_nop 0
	v_mul_f32_e32 v3, 0x4f7ffffe, v3
	v_cvt_u32_f32_e32 v3, v3
	v_mul_lo_u32 v5, v5, v3
	v_mul_hi_u32 v5, v3, v5
	v_add_u32_e32 v3, v3, v5
	s_waitcnt vmcnt(0) lgkmcnt(0)
	v_mul_hi_u32 v3, v4, v3
	v_mul_lo_u32 v5, v3, v2
	v_sub_u32_e32 v5, v4, v5
	v_cmp_ge_u32_e32 vcc, v5, v2
	v_add_u32_e32 v6, 1, v3
	s_nop 0
	v_cndmask_b32_e32 v3, v3, v6, vcc
	v_sub_u32_e32 v6, v5, v2
	v_cndmask_b32_e32 v5, v5, v6, vcc
	v_cmp_ge_u32_e32 vcc, v5, v2
	v_add_u32_e32 v5, 1, v3
	v_add_u32_e32 v6, 1, v4
	v_cndmask_b32_e32 v3, v3, v5, vcc
	v_mad_u64_u32 v[4:5], s[0:1], v2, v3, v[2:3]
	v_cmp_ne_u32_e32 vcc, v6, v4
	s_and_saveexec_b64 s[0:1], vcc
	s_xor_b64 s[0:1], exec, s[0:1]
	s_cbranch_execz .LBB0_363
	v_mul_lo_u32 v6, v0, v3
	s_add_u32 s6, s58, 0x22f23400
	s_addc_u32 s7, s59, 0
	v_add_u32_e32 v6, v6, v0
	v_mov_b64_e32 v[4:5], s[6:7]
	flat_load_dword v0, v[4:5] sc1
	s_waitcnt vmcnt(0) lgkmcnt(0)
	v_cmp_lt_u32_e32 vcc, v0, v6
	s_and_saveexec_b64 s[4:5], vcc
	s_cbranch_execz .LBB0_362
	s_add_u32 s8, s58, 0x22f20200
	s_addc_u32 s9, s59, 0
	s_mov_b32 s26, 1
	s_mov_b64 s[10:11], 0
	s_branch .LBB0_354

; DI unsigned xb_ld(unsigned* p) { return __hip_atomic_load(p, __ATOMIC_RELAXED, __HIP_MEMORY_SCOPE_AGENT); }
; #define XB_SPIN(cond, bar) do { unsigned _sp = 0; while (cond) { __builtin_amdgcn_s_sleep(1); \
;     if ((++_sp & 255u) == 0u) { if (xb_ld(&(bar)[XB_TMO])) break; if (_sp > XB_SPIN_CAP) { atomicAdd(&(bar)[XB_TMO], 1u); break; } } } } while (0)
; DI void xcd_barrier(unsigned* bar, volatile LAS unsigned* st) {
;     ...
;       XB_SPIN(xb_ld(&bar[XB_XGEN(x)]) == gen, bar);
.LBB0_358:
	s_andn2_b64 s[14:15], s[14:15], exec
	s_and_b64 s[20:21], s[20:21], exec
	s_or_b64 s[14:15], s[14:15], s[20:21]
	s_and_saveexec_b64 s[20:21], s[18:19]
	s_cbranch_execz .LBB0_353
	v_mov_b64_e32 v[4:5], s[6:7]
	flat_load_dword v0, v[4:5] sc1
	s_add_i32 s26, s26, 1
	s_or_b64 s[14:15], s[14:15], exec
	s_waitcnt vmcnt(0) lgkmcnt(0)
	v_cmp_ge_u32_e32 vcc, v0, v6
	s_orn2_b64 s[16:17], vcc, exec
	s_branch .LBB0_353

; DI unsigned xb_add(unsigned* p, unsigned v) { return __hip_atomic_fetch_add(p, v, __ATOMIC_RELAXED, __HIP_MEMORY_SCOPE_AGENT); }
; DI void xcd_barrier(unsigned* bar, volatile LAS unsigned* st) {
;     ...
;       __builtin_amdgcn_fence(__ATOMIC_ACQUIRE, "agent");
;       xb_add(&bar[XB_XGEN(x)], 1u);
;       asm volatile("s_waitcnt vmcnt(0)" ::: "memory");
.LBB0_378:
	s_or_b64 exec, exec, s[0:1]
	v_mov_b32_e32 v0, s25
	v_add_co_u32_e32 v2, vcc, 0x2000, v0
	v_mov_b32_e32 v0, s24
	s_nop 0
	v_addc_co_u32_e32 v3, vcc, 0, v0, vcc
	s_waitcnt vmcnt(0) lgkmcnt(0)
	buffer_inv sc1
	s_waitcnt vmcnt(0)

; DI unsigned xb_ld(unsigned* p) { return __hip_atomic_load(p, __ATOMIC_RELAXED, __HIP_MEMORY_SCOPE_AGENT); }
; DI unsigned xb_add(unsigned* p, unsigned v) { return __hip_atomic_fetch_add(p, v, __ATOMIC_RELAXED, __HIP_MEMORY_SCOPE_AGENT); }
; #define XB_SPIN(cond, bar) do { unsigned _sp = 0; while (cond) { __builtin_amdgcn_s_sleep(1); \
;     if ((++_sp & 255u) == 0u) { if (xb_ld(&(bar)[XB_TMO])) break; if (_sp > XB_SPIN_CAP) { atomicAdd(&(bar)[XB_TMO], 1u); break; } } } } while (0)
; DI void xcd_barrier(unsigned* bar, volatile LAS unsigned* st) {
;     ...
;     const unsigned old = xb_add(&bar[XB_XSUB(x)], 1u);
;     const unsigned gen = old / nloc;
;     if (old + 1u == (gen + 1u) * nloc) {
;       __builtin_amdgcn_fence(__ATOMIC_RELEASE, "agent");
;       asm volatile("s_waitcnt vmcnt(0)" ::: "memory");
;       const unsigned og = xb_add(&bar[XB_TOP], 1u);
;       const unsigned tg = og / nx;
;       if (og + 1u == (tg + 1u) * nx) xb_add(&bar[XB_TOPGEN], 1u);
;       else XB_SPIN(xb_ld(&bar[XB_TOPGEN]) == tg, bar);
;       __builtin_amdgcn_fence(__ATOMIC_ACQUIRE, "agent");
;       xb_add(&bar[XB_XGEN(x)], 1u);
;       asm volatile("s_waitcnt vmcnt(0)" ::: "memory");
;     } else {
;       XB_SPIN(xb_ld(&bar[XB_XGEN(x)]) == gen, bar);
.LBB0_407:
	s_lshl_b32 s0, s2, 8
	s_add_u32 s0, s58, s0
	s_addc_u32 s1, s59, 0
	v_mov_b32_e32 v3, s0
	v_add_co_u32_e32 v4, vcc, 0x22f21000, v3
	v_mov_b32_e32 v3, s1
	s_nop 0
	v_addc_co_u32_e32 v5, vcc, 0, v3, vcc
	flat_atomic_add v4, v[4:5], v187 offset:1024 sc0
	v_cvt_f32_u32_e32 v3, v2
	v_sub_u32_e32 v5, 0, v2
	s_add_u32 s3, s0, 0x22f20000
	s_addc_u32 s2, s1, 0
	v_rcp_iflag_f32_e32 v3, v3
	s_nop 0
	v_mul_f32_e32 v3, 0x4f7ffffe, v3
	v_cvt_u32_f32_e32 v3, v3
	v_mul_lo_u32 v5, v5, v3
	v_mul_hi_u32 v5, v3, v5
	v_add_u32_e32 v3, v3, v5
	s_waitcnt vmcnt(0) lgkmcnt(0)
	v_mul_hi_u32 v3, v4, v3
	v_mul_lo_u32 v5, v3, v2
	v_sub_u32_e32 v5, v4, v5
	v_cmp_ge_u32_e32 vcc, v5, v2
	v_add_u32_e32 v6, 1, v3
	s_nop 0
	v_cndmask_b32_e32 v3, v3, v6, vcc
	v_sub_u32_e32 v6, v5, v2
	v_cndmask_b32_e32 v5, v5, v6, vcc
	v_cmp_ge_u32_e32 vcc, v5, v2
	v_add_u32_e32 v5, 1, v3
	v_add_u32_e32 v6, 1, v4
	v_cndmask_b32_e32 v3, v3, v5, vcc
	v_mad_u64_u32 v[4:5], s[0:1], v2, v3, v[2:3]
	v_cmp_ne_u32_e32 vcc, v6, v4
	s_and_saveexec_b64 s[0:1], vcc
	s_xor_b64 s[0:1], exec, s[0:1]
	s_cbranch_execz .LBB0_420
	v_mul_lo_u32 v6, v0, v3
	s_add_u32 s6, s58, 0x22f23400
	s_addc_u32 s7, s59, 0
	v_add_u32_e32 v6, v6, v0
	v_mov_b64_e32 v[4:5], s[6:7]
	flat_load_dword v0, v[4:5] sc1
	s_waitcnt vmcnt(0) lgkmcnt(0)
	v_cmp_lt_u32_e32 vcc, v0, v6
	s_and_saveexec_b64 s[4:5], vcc
	s_cbranch_execz .LBB0_419
	s_add_u32 s8, s58, 0x22f20200
	s_addc_u32 s9, s59, 0
	s_mov_b32 s24, 1
	s_mov_b64 s[10:11], 0
	s_branch .LBB0_411

; DI unsigned xb_ld(unsigned* p) { return __hip_atomic_load(p, __ATOMIC_RELAXED, __HIP_MEMORY_SCOPE_AGENT); }
; #define XB_SPIN(cond, bar) do { unsigned _sp = 0; while (cond) { __builtin_amdgcn_s_sleep(1); \
;     if ((++_sp & 255u) == 0u) { if (xb_ld(&(bar)[XB_TMO])) break; if (_sp > XB_SPIN_CAP) { atomicAdd(&(bar)[XB_TMO], 1u); break; } } } } while (0)
; DI void xcd_barrier(unsigned* bar, volatile LAS unsigned* st) {
;     ...
;       XB_SPIN(xb_ld(&bar[XB_XGEN(x)]) == gen, bar);
.LBB0_415:
	s_andn2_b64 s[14:15], s[14:15], exec
	s_and_b64 s[20:21], s[20:21], exec
	s_or_b64 s[14:15], s[14:15], s[20:21]
	s_and_saveexec_b64 s[20:21], s[18:19]
	s_cbranch_execz .LBB0_410
	v_mov_b64_e32 v[4:5], s[6:7]
	flat_load_dword v0, v[4:5] sc1
	s_add_i32 s24, s24, 1
	s_or_b64 s[14:15], s[14:15], exec
	s_waitcnt vmcnt(0) lgkmcnt(0)
	v_cmp_ge_u32_e32 vcc, v0, v6
	s_orn2_b64 s[16:17], vcc, exec
	s_branch .LBB0_410

; DI unsigned xb_ld(unsigned* p) { return __hip_atomic_load(p, __ATOMIC_RELAXED, __HIP_MEMORY_SCOPE_AGENT); }
; DI unsigned xb_add(unsigned* p, unsigned v) { return __hip_atomic_fetch_add(p, v, __ATOMIC_RELAXED, __HIP_MEMORY_SCOPE_AGENT); }
; #define XB_SPIN(cond, bar) do { unsigned _sp = 0; while (cond) { __builtin_amdgcn_s_sleep(1); \
;     if ((++_sp & 255u) == 0u) { if (xb_ld(&(bar)[XB_TMO])) break; if (_sp > XB_SPIN_CAP) { atomicAdd(&(bar)[XB_TMO], 1u); break; } } } } while (0)
; DI void xcd_barrier(unsigned* bar, volatile LAS unsigned* st) {
;     ...
;     const unsigned old = xb_add(&bar[XB_XSUB(x)], 1u);
;     const unsigned gen = old / nloc;
;     if (old + 1u == (gen + 1u) * nloc) {
;       __builtin_amdgcn_fence(__ATOMIC_RELEASE, "agent");
;       asm volatile("s_waitcnt vmcnt(0)" ::: "memory");
;       const unsigned og = xb_add(&bar[XB_TOP], 1u);
;       const unsigned tg = og / nx;
;       if (og + 1u == (tg + 1u) * nx) xb_add(&bar[XB_TOPGEN], 1u);
;       else XB_SPIN(xb_ld(&bar[XB_TOPGEN]) == tg, bar);
;       __builtin_amdgcn_fence(__ATOMIC_ACQUIRE, "agent");
;       xb_add(&bar[XB_XGEN(x)], 1u);
;       asm volatile("s_waitcnt vmcnt(0)" ::: "memory");
;     } else {
;       XB_SPIN(xb_ld(&bar[XB_XGEN(x)]) == gen, bar);
.LBB0_544:
	s_lshl_b32 s0, s3, 8
	s_add_u32 s0, s58, s0
	s_addc_u32 s1, s59, 0
	v_mov_b32_e32 v3, s0
	v_add_co_u32_e32 v4, vcc, 0x22f21000, v3
	v_mov_b32_e32 v3, s1
	s_nop 0
	v_addc_co_u32_e32 v5, vcc, 0, v3, vcc
	flat_atomic_add v4, v[4:5], v187 offset:1024 sc0
	v_cvt_f32_u32_e32 v3, v2
	v_sub_u32_e32 v5, 0, v2
	s_add_u32 s24, s0, 0x22f20000
	s_addc_u32 s3, s1, 0
	v_rcp_iflag_f32_e32 v3, v3
	s_nop 0
	v_mul_f32_e32 v3, 0x4f7ffffe, v3
	v_cvt_u32_f32_e32 v3, v3
	v_mul_lo_u32 v5, v5, v3
	v_mul_hi_u32 v5, v3, v5
	v_add_u32_e32 v3, v3, v5
	s_waitcnt vmcnt(0) lgkmcnt(0)
	v_mul_hi_u32 v3, v4, v3
	v_mul_lo_u32 v5, v3, v2
	v_sub_u32_e32 v5, v4, v5
	v_cmp_ge_u32_e32 vcc, v5, v2
	v_add_u32_e32 v6, 1, v3
	s_nop 0
	v_cndmask_b32_e32 v3, v3, v6, vcc
	v_sub_u32_e32 v6, v5, v2
	v_cndmask_b32_e32 v5, v5, v6, vcc
	v_cmp_ge_u32_e32 vcc, v5, v2
	v_add_u32_e32 v5, 1, v3
	v_add_u32_e32 v6, 1, v4
	v_cndmask_b32_e32 v3, v3, v5, vcc
	v_mad_u64_u32 v[4:5], s[0:1], v2, v3, v[2:3]
	v_cmp_ne_u32_e32 vcc, v6, v4
	s_and_saveexec_b64 s[0:1], vcc
	s_xor_b64 s[0:1], exec, s[0:1]
	s_cbranch_execz .LBB0_557
	v_mul_lo_u32 v6, v0, v3
	s_add_u32 s6, s58, 0x22f23400
	s_addc_u32 s7, s59, 0
	v_add_u32_e32 v6, v6, v0
	v_mov_b64_e32 v[4:5], s[6:7]
	flat_load_dword v0, v[4:5] sc1
	s_waitcnt vmcnt(0) lgkmcnt(0)
	v_cmp_lt_u32_e32 vcc, v0, v6
	s_and_saveexec_b64 s[4:5], vcc
	s_cbranch_execz .LBB0_556
	s_add_u32 s8, s58, 0x22f20200
	s_addc_u32 s9, s59, 0
	s_mov_b32 s25, 1
	s_mov_b64 s[10:11], 0
	s_branch .LBB0_548

; DI unsigned xb_ld(unsigned* p) { return __hip_atomic_load(p, __ATOMIC_RELAXED, __HIP_MEMORY_SCOPE_AGENT); }
; #define XB_SPIN(cond, bar) do { unsigned _sp = 0; while (cond) { __builtin_amdgcn_s_sleep(1); \
;     if ((++_sp & 255u) == 0u) { if (xb_ld(&(bar)[XB_TMO])) break; if (_sp > XB_SPIN_CAP) { atomicAdd(&(bar)[XB_TMO], 1u); break; } } } } while (0)
; DI void xcd_barrier(unsigned* bar, volatile LAS unsigned* st) {
;     ...
;       XB_SPIN(xb_ld(&bar[XB_XGEN(x)]) == gen, bar);
.LBB0_552:
	s_andn2_b64 s[14:15], s[14:15], exec
	s_and_b64 s[20:21], s[20:21], exec
	s_or_b64 s[14:15], s[14:15], s[20:21]
	s_and_saveexec_b64 s[20:21], s[18:19]
	s_cbranch_execz .LBB0_547
	v_mov_b64_e32 v[4:5], s[6:7]
	flat_load_dword v0, v[4:5] sc1
	s_add_i32 s25, s25, 1
	s_or_b64 s[14:15], s[14:15], exec
	s_waitcnt vmcnt(0) lgkmcnt(0)
	v_cmp_ge_u32_e32 vcc, v0, v6
	s_orn2_b64 s[16:17], vcc, exec
	s_branch .LBB0_547

; DI unsigned xb_add(unsigned* p, unsigned v) { return __hip_atomic_fetch_add(p, v, __ATOMIC_RELAXED, __HIP_MEMORY_SCOPE_AGENT); }
; DI void xcd_barrier(unsigned* bar, volatile LAS unsigned* st) {
;     ...
;       __builtin_amdgcn_fence(__ATOMIC_ACQUIRE, "agent");
;       xb_add(&bar[XB_XGEN(x)], 1u);
;       asm volatile("s_waitcnt vmcnt(0)" ::: "memory");
.LBB0_572:
	s_or_b64 exec, exec, s[0:1]
	v_mov_b32_e32 v0, s24
	v_add_co_u32_e32 v2, vcc, 0x2000, v0
	v_mov_b32_e32 v0, s3
	s_nop 0
	v_addc_co_u32_e32 v3, vcc, 0, v0, vcc
	s_waitcnt vmcnt(0) lgkmcnt(0)
	buffer_inv sc1
	s_waitcnt vmcnt(0)

; DI unsigned xb_ld(unsigned* p) { return __hip_atomic_load(p, __ATOMIC_RELAXED, __HIP_MEMORY_SCOPE_AGENT); }
; DI unsigned xb_add(unsigned* p, unsigned v) { return __hip_atomic_fetch_add(p, v, __ATOMIC_RELAXED, __HIP_MEMORY_SCOPE_AGENT); }
; #define XB_SPIN(cond, bar) do { unsigned _sp = 0; while (cond) { __builtin_amdgcn_s_sleep(1); \
;     if ((++_sp & 255u) == 0u) { if (xb_ld(&(bar)[XB_TMO])) break; if (_sp > XB_SPIN_CAP) { atomicAdd(&(bar)[XB_TMO], 1u); break; } } } } while (0)
; DI void xcd_barrier(unsigned* bar, volatile LAS unsigned* st) {
;     ...
;     const unsigned old = xb_add(&bar[XB_XSUB(x)], 1u);
;     const unsigned gen = old / nloc;
;     if (old + 1u == (gen + 1u) * nloc) {
;       __builtin_amdgcn_fence(__ATOMIC_RELEASE, "agent");
;       asm volatile("s_waitcnt vmcnt(0)" ::: "memory");
;       const unsigned og = xb_add(&bar[XB_TOP], 1u);
;       const unsigned tg = og / nx;
;       if (og + 1u == (tg + 1u) * nx) xb_add(&bar[XB_TOPGEN], 1u);
;       else XB_SPIN(xb_ld(&bar[XB_TOPGEN]) == tg, bar);
;       __builtin_amdgcn_fence(__ATOMIC_ACQUIRE, "agent");
;       xb_add(&bar[XB_XGEN(x)], 1u);
;       asm volatile("s_waitcnt vmcnt(0)" ::: "memory");
;     } else {
;       XB_SPIN(xb_ld(&bar[XB_XGEN(x)]) == gen, bar);
.LBB0_848:
	s_lshl_b32 s0, s2, 8
	s_add_u32 s0, s40, s0
	s_addc_u32 s1, s41, 0
	v_mov_b32_e32 v3, s0
	v_add_co_u32_e32 v4, vcc, 0x22f21000, v3
	v_mov_b32_e32 v3, s1
	s_nop 0
	v_addc_co_u32_e32 v5, vcc, 0, v3, vcc
	flat_atomic_add v4, v[4:5], v187 offset:1024 sc0
	v_cvt_f32_u32_e32 v3, v2
	v_sub_u32_e32 v5, 0, v2
	s_add_u32 s3, s0, 0x22f20000
	s_addc_u32 s2, s1, 0
	v_rcp_iflag_f32_e32 v3, v3
	s_nop 0
	v_mul_f32_e32 v3, 0x4f7ffffe, v3
	v_cvt_u32_f32_e32 v3, v3
	v_mul_lo_u32 v5, v5, v3
	v_mul_hi_u32 v5, v3, v5
	v_add_u32_e32 v3, v3, v5
	s_waitcnt vmcnt(0) lgkmcnt(0)
	v_mul_hi_u32 v3, v4, v3
	v_mul_lo_u32 v5, v3, v2
	v_sub_u32_e32 v5, v4, v5
	v_cmp_ge_u32_e32 vcc, v5, v2
	v_add_u32_e32 v6, 1, v3
	s_nop 0
	v_cndmask_b32_e32 v3, v3, v6, vcc
	v_sub_u32_e32 v6, v5, v2
	v_cndmask_b32_e32 v5, v5, v6, vcc
	v_cmp_ge_u32_e32 vcc, v5, v2
	v_add_u32_e32 v5, 1, v3
	v_add_u32_e32 v6, 1, v4
	v_cndmask_b32_e32 v3, v3, v5, vcc
	v_mad_u64_u32 v[4:5], s[0:1], v2, v3, v[2:3]
	v_cmp_ne_u32_e32 vcc, v6, v4
	s_and_saveexec_b64 s[0:1], vcc
	s_xor_b64 s[0:1], exec, s[0:1]
	s_cbranch_execz .LBB0_861
	v_mul_lo_u32 v6, v0, v3
	s_add_u32 s6, s40, 0x22f23400
	s_addc_u32 s7, s41, 0
	v_add_u32_e32 v6, v6, v0
	v_mov_b64_e32 v[4:5], s[6:7]
	flat_load_dword v0, v[4:5] sc1
	s_waitcnt vmcnt(0) lgkmcnt(0)
	v_cmp_lt_u32_e32 vcc, v0, v6
	s_and_saveexec_b64 s[4:5], vcc
	s_cbranch_execz .LBB0_860
	s_add_u32 s8, s40, 0x22f20200
	s_addc_u32 s9, s41, 0
	s_mov_b32 s24, 1
	s_mov_b64 s[10:11], 0
	s_branch .LBB0_852
